# P0 scalar-path transpose loops rewritten with 8 loads in flight (on top of P1 convert batching)
# speedup vs baseline: 1.0329x; 1.0086x over previous
.LBB0_79:
	v_mov_b32_e32 v210, 0
	v_mov_b32_e32 v212, 0
	v_mov_b32_e32 v214, 0
	v_mov_b32_e32 v216, 0
	v_mov_b32_e32 v218, 0
	v_mov_b32_e32 v220, 0
	v_mov_b32_e32 v222, 0
	v_mov_b32_e32 v224, 0
	s_and_saveexec_b64 s[26:27], vcc
	v_add_u32_e32 v226, s28, v11
	v_mad_i64_i32 v[210:211], s[58:59], v226, s49, v[0:1]
	global_load_dword v210, v[210:211], off nt
	v_add3_u32 v226, v11, s28, 2
	v_mad_i64_i32 v[212:213], s[58:59], v226, s49, v[0:1]
	global_load_dword v212, v[212:213], off nt
	v_add3_u32 v226, v11, s28, 4
	v_mad_i64_i32 v[214:215], s[58:59], v226, s49, v[0:1]
	global_load_dword v214, v[214:215], off nt
	v_add3_u32 v226, v11, s28, 6
	v_mad_i64_i32 v[216:217], s[58:59], v226, s49, v[0:1]
	global_load_dword v216, v[216:217], off nt
	v_add3_u32 v226, v11, s28, 8
	v_mad_i64_i32 v[218:219], s[58:59], v226, s49, v[0:1]
	global_load_dword v218, v[218:219], off nt
	v_add3_u32 v226, v11, s28, 10
	v_mad_i64_i32 v[220:221], s[58:59], v226, s49, v[0:1]
	global_load_dword v220, v[220:221], off nt
	v_add3_u32 v226, v11, s28, 12
	v_mad_i64_i32 v[222:223], s[58:59], v226, s49, v[0:1]
	global_load_dword v222, v[222:223], off nt
	v_add3_u32 v226, v11, s28, 14
	v_mad_i64_i32 v[224:225], s[58:59], v226, s49, v[0:1]
	global_load_dword v224, v[224:225], off nt
	s_or_b64 exec, exec, s[26:27]
	s_add_i32 s28, s28, 16
	s_cmp_lg_u32 s28, 64
	s_waitcnt vmcnt(7)
	ds_write_b32 v2, v210
	s_waitcnt vmcnt(6)
	ds_write_b32 v2, v212 offset:264
	s_waitcnt vmcnt(5)
	ds_write_b32 v2, v214 offset:528
	s_waitcnt vmcnt(4)
	ds_write_b32 v2, v216 offset:792
	s_waitcnt vmcnt(3)
	ds_write_b32 v2, v218 offset:1056
	s_waitcnt vmcnt(2)
	ds_write_b32 v2, v220 offset:1320
	s_waitcnt vmcnt(1)
	ds_write_b32 v2, v222 offset:1584
	s_waitcnt vmcnt(0)
	ds_write_b32 v2, v224 offset:1848
	v_add_u32_e32 v2, 0x840, v2
	s_cbranch_scc1 .LBB0_79
	s_branch .LBB0_102

.LBB0_117:
	v_mov_b32_e32 v210, 0
	v_mov_b32_e32 v212, 0
	v_mov_b32_e32 v214, 0
	v_mov_b32_e32 v216, 0
	v_mov_b32_e32 v218, 0
	v_mov_b32_e32 v220, 0
	v_mov_b32_e32 v222, 0
	v_mov_b32_e32 v224, 0
	s_and_saveexec_b64 s[12:13], vcc
	v_add_u32_e32 v226, s14, v11
	v_mad_i64_i32 v[210:211], s[26:27], v226, s49, v[2:3]
	global_load_dword v210, v[210:211], off nt
	v_add3_u32 v226, v11, s14, 2
	v_mad_i64_i32 v[212:213], s[26:27], v226, s49, v[2:3]
	global_load_dword v212, v[212:213], off nt
	v_add3_u32 v226, v11, s14, 4
	v_mad_i64_i32 v[214:215], s[26:27], v226, s49, v[2:3]
	global_load_dword v214, v[214:215], off nt
	v_add3_u32 v226, v11, s14, 6
	v_mad_i64_i32 v[216:217], s[26:27], v226, s49, v[2:3]
	global_load_dword v216, v[216:217], off nt
	v_add3_u32 v226, v11, s14, 8
	v_mad_i64_i32 v[218:219], s[26:27], v226, s49, v[2:3]
	global_load_dword v218, v[218:219], off nt
	v_add3_u32 v226, v11, s14, 10
	v_mad_i64_i32 v[220:221], s[26:27], v226, s49, v[2:3]
	global_load_dword v220, v[220:221], off nt
	v_add3_u32 v226, v11, s14, 12
	v_mad_i64_i32 v[222:223], s[26:27], v226, s49, v[2:3]
	global_load_dword v222, v[222:223], off nt
	v_add3_u32 v226, v11, s14, 14
	v_mad_i64_i32 v[224:225], s[26:27], v226, s49, v[2:3]
	global_load_dword v224, v[224:225], off nt
	s_or_b64 exec, exec, s[12:13]
	s_add_i32 s14, s14, 16
	s_cmp_lg_u32 s14, 64
	s_waitcnt vmcnt(7)
	ds_write_b32 v6, v210
	s_waitcnt vmcnt(6)
	ds_write_b32 v6, v212 offset:264
	s_waitcnt vmcnt(5)
	ds_write_b32 v6, v214 offset:528
	s_waitcnt vmcnt(4)
	ds_write_b32 v6, v216 offset:792
	s_waitcnt vmcnt(3)
	ds_write_b32 v6, v218 offset:1056
	s_waitcnt vmcnt(2)
	ds_write_b32 v6, v220 offset:1320
	s_waitcnt vmcnt(1)
	ds_write_b32 v6, v222 offset:1584
	s_waitcnt vmcnt(0)
	ds_write_b32 v6, v224 offset:1848
	v_add_u32_e32 v6, 0x840, v6
	s_cbranch_scc1 .LBB0_117
